# no-embed: all weight conversion done in P0 prologue path, P4 recurrence runs without embedded conversion (uses baseline's G!=256 code path)
# speedup vs baseline: 1.0001x; 1.0001x over previous
; #define GAS __attribute__((address_space(1)))
; #define LAS __attribute__((address_space(3)))
; __device__ __forceinline__ void p0_transpose_item(const float* W, int N, bf16* WT, int ldt, int rowmode, LAS float* scr, int kb, int nb, int lane, const float* kgain) {
;     const int k0 = 64 * kb, n0 = 32 * nb;
;     const int lk = lane >> 3, ln = (lane & 7) * 4;
; #pragma unroll
;     for (int i = 0; i < 8; ++i) { const int kk = 8 * i + lk; f32x4 v = __builtin_nontemporal_load((const GAS f32x4*)(W + (size_t)(k0 + kk) * N + n0 + ln)); if (kgain) v = v * kgain[k0 + kk];
;         scr[kk * 33 + ln] = v[0]; scr[kk * 33 + ln + 1] = v[1]; scr[kk * 33 + ln + 2] = v[2]; scr[kk * 33 + ln + 3] = v[3]; }
; __global__ void __launch_bounds__(NWAVES * 64, 2) fwd(Args args) {
;     ...
;     const int gw = F.vcu * NWAVES + F.wave, NGW = F.G * NWAVES;
;     const bool embed = (F.G == 256);
;     const int gt = F.vcu * (NWAVES * 64) + F.tid, NGT = F.G * NWAVES * 64;
;     if (IN(0)) {
;         LAS float* scr = (LAS float*)(F.lds + RING_OFF + F.wave * 16384);
;         p0_transpose_matrix(w_in, D, NIN, WinT, D, 3, scr, gw, NGW, F.lane);
.LBB0_9:
	s_or_b64 exec, exec, s[0:1]
	s_add_u32 s10, s68, 0x9100000
	s_addc_u32 s11, s69, 0
	s_add_u32 s12, s68, 0x100000
	s_addc_u32 s13, s69, 0
	s_lshr_b32 s1, s3, 6
	s_lshl_b32 s0, s88, 3
	s_add_i32 s80, s0, s1
	s_lshl_b32 s82, s74, 3
	s_cmpk_eq_i32 s74, 0x100
	s_cselect_b64 s[34:35], -1, 0
	s_cmpk_lg_i32 s74, 0x101
	v_writelane_b32 v244, s1, 10
	s_cselect_b64 s[0:1], -1, 0
	s_cmp_lt_i32 s70, 1
	s_cselect_b64 s[4:5], -1, 0
	s_cmp_gt_i32 s71, 0
	s_cselect_b64 s[6:7], -1, 0
	s_and_b64 s[4:5], s[4:5], s[6:7]
	s_andn2_b64 vcc, exec, s[4:5]
	v_and_b32_e32 v1, 63, v0
	s_cbranch_vccnz .LBB0_130
	v_readlane_b32 s4, v244, 10
	s_lshl_b32 s6, s4, 14
	v_lshrrev_b32_e32 v22, 3, v1
	v_and_b32_e32 v4, 7, v0
	s_cmp_lt_i32 s80, 0x9000
	v_lshlrev_b32_e32 v2, 2, v4
	v_mov_b32_e32 v11, 0
	v_or_b32_e32 v32, 8, v22
	v_or_b32_e32 v31, 16, v22
	v_or_b32_e32 v30, 24, v22
	v_or_b32_e32 v21, 32, v22
	v_or_b32_e32 v20, 40, v22
	v_or_b32_e32 v18, 48, v22
	v_or_b32_e32 v17, 56, v22
	v_lshlrev_b32_e32 v10, 3, v4
	s_cbranch_scc1 .LBB0_12
	s_movk_i32 s4, 0x84
	v_mov_b32_e32 v3, 0x420
	v_mad_u32_u24 v9, v22, s4, v3
	v_mov_b32_e32 v3, 0x840
	v_mad_u32_u24 v14, v22, s4, v3
	v_mov_b32_e32 v3, 0xc60
	v_mad_u32_u24 v15, v22, s4, v3
	v_mov_b32_e32 v3, 0x1080
	v_mad_u32_u24 v16, v22, s4, v3
	v_mov_b32_e32 v3, 0x14a0
	v_mad_u32_u24 v19, v22, s4, v3
	v_mov_b32_e32 v3, 0x18c0
	v_mad_u32_u24 v40, v22, s4, v3
	v_mov_b32_e32 v3, 0x1ce0
	v_mul_u32_u24_e32 v8, 0x84, v22
	v_or_b32_e32 v23, 8, v22
	v_or_b32_e32 v24, 16, v22
	v_or_b32_e32 v25, 24, v22
	v_or_b32_e32 v26, 32, v22
	v_or_b32_e32 v27, 40, v22
	v_or_b32_e32 v28, 48, v22
	v_or_b32_e32 v29, 56, v22
	v_mad_u32_u24 v41, v22, s4, v3
	v_mul_u32_u24_e32 v33, 0x420, v4
	s_add_i32 s14, s6, 0
	v_lshlrev_b32_e32 v12, 2, v2
	s_cbranch_execz .LBB0_13
	s_branch .LBB0_16

;     ...
;         const int cga = (2 * blk) * 2048 + cvslot, cgb = cga + 2048; const bool cva_on = FULL && cv && cga < CV_TOTAL, cvb_on = FULL && cv && cgb < CV_TOTAL;
;         if (cva_on) { cia = conv_decode(cv, cga); conv_load(cia, lane, cva); }
;         if (cvb_on) { cib = conv_decode(cv, cgb); conv_load(cib, lane, cvb); }
.LBB0_558:
	s_add_i32 s26, s89, 0xfffff000
	s_cmp_lt_i32 s26, 0xfe50
	s_cselect_b64 s[0:1], -1, 0
	s_mov_b64 s[0:1], 0
	v_cndmask_b32_e64 v66, 0, 1, s[0:1]
	v_cmp_ne_u32_e64 s[30:31], 1, v66
	s_andn2_b64 vcc, exec, s[0:1]
	s_cbranch_vccnz .LBB0_567
	s_cmpk_gt_i32 s26, 0x1fff
	s_cselect_b64 s[0:1], -1, 0
	s_cmpk_gt_i32 s26, 0x3fff
	v_cndmask_b32_e64 v66, 0, 1, s[0:1]
	s_cselect_b64 s[0:1], -1, 0
	s_cmpk_gt_i32 s26, 0x7fff
	v_cndmask_b32_e64 v67, 0, 1, s[0:1]
	s_cselect_b64 s[0:1], -1, 0
	v_readfirstlane_b32 s20, v66
	v_readfirstlane_b32 s21, v67
	s_cmp_lg_u64 s[0:1], 0
	s_addc_u32 s27, s20, s21
	s_cmp_lt_i32 s27, 1
	s_mov_b32 s28, s27
	s_cbranch_scc1 .LBB0_564
	s_cmp_eq_u32 s27, 1
	s_mov_b64 s[0:1], -1
	s_cbranch_scc1 .LBB0_562
	s_cmp_eq_u32 s27, 2
	s_cselect_b32 s28, s84, 0xffff8000
	s_mov_b64 s[0:1], 0

;     ...
;         const int cga = (2 * blk) * 2048 + cvslot, cgb = cga + 2048; const bool cva_on = FULL && cv && cga < CV_TOTAL, cvb_on = FULL && cv && cgb < CV_TOTAL;
;         if (cva_on) { cia = conv_decode(cv, cga); conv_load(cia, lane, cva); }
;         if (cvb_on) { cib = conv_decode(cv, cgb); conv_load(cib, lane, cvb); }
.LBB0_567:
.LBB0_568:
	s_cmp_lt_i32 s26, 0xf650
	s_cselect_b64 s[0:1], -1, 0
	s_mov_b64 s[0:1], 0
	v_cndmask_b32_e64 v66, 0, 1, s[0:1]
	v_cmp_ne_u32_e64 s[28:29], 1, v66
	s_andn2_b64 vcc, exec, s[0:1]
	s_cbranch_vccnz .LBB0_577
	s_cmpk_gt_i32 s26, 0x17ff
	s_cselect_b64 s[0:1], -1, 0
	s_cmpk_gt_i32 s26, 0x37ff
	v_cndmask_b32_e64 v66, 0, 1, s[0:1]
	s_cselect_b64 s[0:1], -1, 0
	s_cmpk_gt_i32 s26, 0x77ff
	v_cndmask_b32_e64 v67, 0, 1, s[0:1]
	s_cselect_b64 s[0:1], -1, 0
	v_readfirstlane_b32 s20, v66
	v_readfirstlane_b32 s21, v67
	s_cmp_lg_u64 s[0:1], 0
	s_addc_u32 s26, s20, s21
	s_cmp_lt_i32 s26, 1
	s_mov_b32 s27, s26
	s_cbranch_scc1 .LBB0_574
	s_cmp_eq_u32 s26, 1
	s_mov_b64 s[0:1], -1
	s_cbranch_scc1 .LBB0_572
	s_cmp_eq_u32 s26, 2
	s_cselect_b32 s27, s84, 0xffff8000
	s_mov_b64 s[0:1], 0

;     ...
;         const int cga = (2 * blk) * 2048 + cvslot, cgb = cga + 2048; const bool cva_on = FULL && cv && cga < CV_TOTAL, cvb_on = FULL && cv && cgb < CV_TOTAL;
;         if (cva_on) { cia = conv_decode(cv, cga); conv_load(cia, lane, cva); }
;         if (cvb_on) { cib = conv_decode(cv, cgb); conv_load(cib, lane, cvb); }
.LBB0_604:
	s_cmp_lt_i32 s89, 0xfe50
	s_cselect_b64 s[0:1], -1, 0
	s_mov_b64 s[0:1], 0
	v_cndmask_b32_e64 v66, 0, 1, s[0:1]
	v_cmp_ne_u32_e64 s[30:31], 1, v66
	s_andn2_b64 vcc, exec, s[0:1]
	s_cbranch_vccnz .LBB0_613
	s_cmpk_gt_i32 s89, 0x1fff
	s_cselect_b64 s[0:1], -1, 0
	s_cmpk_gt_i32 s89, 0x3fff
	v_cndmask_b32_e64 v66, 0, 1, s[0:1]
	s_cselect_b64 s[0:1], -1, 0
	s_cmpk_gt_i32 s89, 0x7fff
	v_cndmask_b32_e64 v67, 0, 1, s[0:1]
	s_cselect_b64 s[0:1], -1, 0
	v_readfirstlane_b32 s20, v66
	v_readfirstlane_b32 s21, v67
	s_cmp_lg_u64 s[0:1], 0
	s_addc_u32 s28, s20, s21
	s_cmp_lt_i32 s28, 1
	s_mov_b32 s29, s28
	s_cbranch_scc1 .LBB0_610
	s_cmp_eq_u32 s28, 1
	s_mov_b64 s[0:1], -1
	s_cbranch_scc1 .LBB0_608
	s_cmp_eq_u32 s28, 2
	s_cselect_b32 s29, s84, 0xffff8000
	s_mov_b64 s[0:1], 0

;     ...
;         const int cga = (2 * blk) * 2048 + cvslot, cgb = cga + 2048; const bool cva_on = FULL && cv && cga < CV_TOTAL, cvb_on = FULL && cv && cgb < CV_TOTAL;
;         if (cva_on) { cia = conv_decode(cv, cga); conv_load(cia, lane, cva); }
;         if (cvb_on) { cib = conv_decode(cv, cgb); conv_load(cib, lane, cvb); }
.LBB0_613:
.LBB0_614:
	s_cmp_lt_i32 s89, 0xf650
	s_cselect_b64 s[20:21], -1, 0
	s_mov_b64 s[20:21], 0
	v_cndmask_b32_e64 v66, 0, 1, s[20:21]
	v_cmp_ne_u32_e64 s[28:29], 1, v66
	s_andn2_b64 vcc, exec, s[20:21]
	s_cbranch_vccnz .LBB0_623
	s_cmpk_gt_i32 s89, 0x17ff
	s_cselect_b64 s[20:21], -1, 0
	s_cmpk_gt_i32 s89, 0x37ff
	v_cndmask_b32_e64 v66, 0, 1, s[20:21]
	s_cselect_b64 s[20:21], -1, 0
	s_cmpk_gt_i32 s89, 0x77ff
	v_cndmask_b32_e64 v67, 0, 1, s[20:21]
	s_cselect_b64 s[20:21], -1, 0
	v_readfirstlane_b32 s37, v66
	v_readfirstlane_b32 s72, v67
	s_cmp_lg_u64 s[20:21], 0
	s_addc_u32 s37, s37, s72
	s_cmp_lt_i32 s37, 1
	s_mov_b32 s77, s37
	s_cbranch_scc1 .LBB0_620
	s_cmp_eq_u32 s37, 1
	s_mov_b64 s[72:73], -1
	s_cbranch_scc1 .LBB0_618
	s_cmp_eq_u32 s37, 2
	s_cselect_b32 s77, s84, 0xffff8000
	s_mov_b64 s[72:73], 0
